# static s_setprio 1 for waves 4-7 during the dilated-attention and qknorm phases (same-program wave pairs)
# baseline (speedup 1.0000x reference)
.LBB0_272:
	s_cmp_lt_i32 s98, 4
	s_cselect_b64 s[0:1], -1, 0
	s_cmp_gt_i32 s99, 3
	s_cselect_b64 s[4:5], -1, 0
	s_and_b64 s[0:1], s[0:1], s[4:5]
	s_andn2_b64 vcc, exec, s[0:1]
	s_cbranch_vccnz .LBB0_288
	v_mbcnt_hi_u32_b32 v2, -1, v147
	v_readlane_b32 s0, v255, 3
	v_mov_b32_e32 v3, v2
	s_cmpk_gt_i32 s0, 0x7fff
	v_readlane_b32 s1, v255, 4
	s_cbranch_scc1 .LBB0_276
	v_and_b32_e32 v7, 3, v3
	v_ashrrev_i32_e32 v9, 2, v3
	v_lshlrev_b32_e32 v64, 4, v3
	v_lshlrev_b32_e32 v3, 6, v3
	s_movk_i32 s0, 0xc0
	v_and_b32_e32 v8, 64, v3
	v_and_b32_e32 v3, 64, v2
	v_mul_lo_u32 v10, v9, s0
	v_lshlrev_b32_e32 v62, 5, v7
	v_lshlrev_b32_e32 v6, 3, v7
	v_lshlrev_b32_e32 v11, 7, v7
	v_lshlrev_b32_e32 v12, 4, v7
	v_cmp_gt_u32_e64 s[0:1], 2, v7
	v_cmp_lt_u32_e64 s[4:5], 1, v7
	v_add_u32_e32 v3, 64, v3
	v_xor_b32_e32 v7, 1, v2
	v_cmp_lt_i32_e32 vcc, v7, v3
	s_add_u32 s22, s96, 0x7a00000
	s_addc_u32 s23, s97, 0
	v_cndmask_b32_e32 v7, v2, v7, vcc
	v_lshlrev_b32_e32 v63, 2, v7
	v_xor_b32_e32 v7, 2, v2
	v_cmp_lt_i32_e32 vcc, v7, v3
	s_add_u32 s24, s96, 0x7c00000
	v_readlane_b32 s7, v255, 2
	v_cndmask_b32_e32 v7, v2, v7, vcc
	v_lshlrev_b32_e32 v108, 2, v7
	v_xor_b32_e32 v7, 4, v2
	v_cmp_lt_i32_e32 vcc, v7, v3
	s_addc_u32 s25, s97, 0
	s_lshl_b32 s6, s2, 8
	v_cndmask_b32_e32 v7, v2, v7, vcc
	v_lshlrev_b32_e32 v109, 2, v7
	v_xor_b32_e32 v7, 8, v2
	v_cmp_lt_i32_e32 vcc, v7, v3
	s_lshl_b32 s7, s7, 5
	s_add_i32 s26, s6, s7
	v_cndmask_b32_e32 v7, v2, v7, vcc
	v_lshlrev_b32_e32 v110, 2, v7
	v_xor_b32_e32 v7, 16, v2
	v_cmp_lt_i32_e32 vcc, v7, v3
	v_readlane_b32 s6, v255, 3
	v_mov_b32_e32 v65, 0
	v_cndmask_b32_e32 v7, v2, v7, vcc
	v_lshlrev_b32_e32 v111, 2, v7
	v_xor_b32_e32 v7, 32, v2
	v_cmp_lt_i32_e32 vcc, v7, v3
	v_readlane_b32 s7, v255, 4
	s_mov_b32 s20, s6
	v_cndmask_b32_e32 v2, v2, v7, vcc
	s_ashr_i32 s21, s6, 31
	v_lshlrev_b32_e32 v112, 2, v2
	s_lshl_b64 s[6:7], s[20:21], 13
	v_lshl_or_b32 v2, v9, 9, v11
	v_mov_b32_e32 v3, v65
	v_lshl_add_u64 v[66:67], s[6:7], 0, v[2:3]
	v_or_b32_e32 v2, v10, v6
	v_mov_b32_e32 v3, 0x100
	v_mov_b32_e32 v7, 0x1800
	v_lshl_add_u32 v2, v2, 1, v3
	v_mov_b32_e32 v3, v65
	v_mad_i64_i32 v[70:71], s[10:11], s20, v7, v[2:3]
	v_mov_b32_e32 v2, 0x1a00
	v_add_lshl_u32 v4, v10, v62, 1
	v_mov_b32_e32 v5, v65
	s_mul_hi_i32 s12, s20, 0x1a00
	s_mul_i32 s13, s20, 0x1a00
	v_mad_i64_i32 v[72:73], s[10:11], s20, v2, v[64:65]
	v_lshl_or_b32 v64, v9, 7, v12
	s_mov_b32 s18, s20
	s_ashr_i32 s47, s46, 31
	v_mad_i64_i32 v[68:69], s[8:9], s20, v7, v[4:5]
	v_or_b32_e32 v74, s13, v12
	v_mov_b32_e32 v75, s12
	v_mad_i64_i32 v[76:77], s[12:13], s20, v2, v[64:65]
	v_writelane_b32 v255, s18, 3
	s_lshl_b32 s27, s3, 8
	s_lshl_b64 s[6:7], s[46:47], 13
	s_mul_hi_i32 s9, s46, 0x1800
	s_mul_i32 s8, s46, 0x1800
	s_mul_hi_i32 s11, s46, 0x1a00
	s_mul_i32 s10, s46, 0x1a00
	s_mov_b32 s28, 0x11000000
	s_mov_b64 s[12:13], 0x1e000000
	s_mov_b32 s29, 0x1e000000
	s_mov_b64 s[14:15], 0x2a000000
	s_mov_b32 s30, 0x2a000000
	s_mov_b64 s[16:17], 0x2a000040
	v_mov_b32_e32 v113, 0x358637bd
	v_lshlrev_b32_e32 v64, 2, v62
	v_lshlrev_b32_e32 v78, 2, v6
	v_mov_b32_e32 v79, v65
	v_lshlrev_b32_e32 v80, 2, v8
	v_mov_b32_e32 v81, v65
	v_writelane_b32 v255, s19, 4
	s_mov_b32 s31, s20
	v_readlane_b32 s40, v255, 2
	s_cmp_lt_u32 s40, 4
	s_cbranch_scc1 .Lprio_p3
	s_setprio 1
.Lprio_p3:
.LBB0_275:
	v_lshl_add_u64 v[6:7], s[96:97], 0, v[72:73]
	v_lshl_add_u64 v[2:3], s[96:97], 0, v[68:69]
	v_add_co_u32_e32 v6, vcc, 0x11000000, v6
	s_mov_b64 s[20:21], s[62:63]
	s_mov_b64 s[18:19], s[76:77]
	v_lshl_add_u64 v[186:187], s[76:77], 0, v[80:81]
	global_load_dwordx4 v[190:193], v[186:187], off
	global_load_dwordx4 v[194:197], v[186:187], off offset:16
	global_load_dwordx4 v[198:201], v[186:187], off offset:32
	global_load_dwordx4 v[202:205], v[186:187], off offset:48
	global_load_dwordx4 v[206:209], v[186:187], off offset:64
	global_load_dwordx4 v[210:213], v[186:187], off offset:80
	global_load_dwordx4 v[214:217], v[186:187], off offset:96
	global_load_dwordx4 v[218:221], v[186:187], off offset:112
	global_load_dwordx4 v[222:225], v[186:187], off offset:128
	global_load_dwordx4 v[226:229], v[186:187], off offset:144
	global_load_dwordx4 v[230:233], v[186:187], off offset:160
	global_load_dwordx4 v[234:237], v[186:187], off offset:176
	global_load_dwordx4 v[238:241], v[186:187], off offset:192
	global_load_dwordx4 v[242:245], v[186:187], off offset:208
	global_load_dwordx4 v[246:249], v[186:187], off offset:224
	global_load_dwordx4 v[250:253], v[186:187], off offset:240
	v_lshl_add_u64 v[4:5], v[2:3], 0, s[12:13]
	v_addc_co_u32_e32 v7, vcc, 0, v7, vcc
	global_load_dwordx4 v[48:51], v[4:5], off offset:32
	global_load_dwordx4 v[52:55], v[4:5], off offset:48
	global_load_dwordx4 v[56:59], v[6:7], off
	global_load_dwordx4 v[86:89], v[4:5], off offset:16
	v_add_co_u32_e32 v84, vcc, 0x1e000000, v2
	v_lshl_add_u64 v[4:5], s[96:97], 0, v[74:75]
	s_nop 0
	v_addc_co_u32_e32 v85, vcc, 0, v3, vcc
	global_load_dwordx4 v[90:93], v[84:85], off
	v_add_co_u32_e32 v44, vcc, s28, v4
	v_lshl_add_u64 v[42:43], s[96:97], 0, v[66:67]
	s_nop 0
	v_addc_co_u32_e32 v45, vcc, 0, v5, vcc
	v_add_co_u32_e32 v82, vcc, s30, v42
	v_lshl_add_u64 v[2:3], s[96:97], 0, v[70:71]
	s_nop 0
	v_addc_co_u32_e32 v83, vcc, 0, v43, vcc
	v_add_co_u32_e32 v100, vcc, s29, v2
	s_and_b32 s33, s26, 0x7ffe0
	s_nop 0
	v_addc_co_u32_e32 v101, vcc, 0, v3, vcc
	global_load_dwordx4 v[34:37], v[100:101], off
	global_load_dwordx4 v[38:41], v[100:101], off offset:64
	s_lshl_b32 s33, s33, 2
	s_add_u32 s34, s22, s33
	v_mov_b32_e32 v8, v62
	s_addc_u32 s35, s23, 0
	s_add_u32 s38, s24, s33
	v_lshl_add_u64 v[46:47], v[42:43], 0, s[14:15]
	s_addc_u32 s39, s25, 0
	global_load_dwordx4 v[30:33], v[6:7], off offset:1024
	global_load_dwordx4 v[26:29], v[44:45], off offset:2048
	global_load_dwordx4 v[18:21], v[46:47], off offset:48
	global_load_dwordx4 v[22:25], v[46:47], off offset:32
	global_load_dwordx4 v[10:13], v8, s[34:35]
	global_load_dwordx4 v[2:5], v8, s[34:35] offset:16
	global_load_dwordx4 v[14:17], v8, s[38:39]
	s_nop 0
	global_load_dwordx4 v[6:9], v8, s[38:39] offset:16
	v_lshl_add_u64 v[42:43], v[42:43], 0, s[16:17]
	v_lshl_add_u64 v[142:143], s[20:21], 0, v[78:79]
	s_waitcnt vmcnt(0)
	v_lshlrev_b32_e32 v148, 16, v49
	v_and_b32_e32 v149, 0xffff0000, v49
	v_and_b32_e32 v49, 0xffff0000, v56
	v_lshlrev_b32_e32 v145, 16, v48
	v_and_b32_e32 v146, 0xffff0000, v48
	v_lshlrev_b32_e32 v48, 16, v56
	v_mul_f32_e32 v49, v49, v49
	v_lshlrev_b32_e32 v150, 16, v50
	v_and_b32_e32 v151, 0xffff0000, v50
	v_lshlrev_b32_e32 v50, 16, v57
	v_fmac_f32_e32 v49, v48, v48
	v_lshlrev_b32_e32 v152, 16, v51
	v_and_b32_e32 v153, 0xffff0000, v51
	v_and_b32_e32 v51, 0xffff0000, v57
	v_fmac_f32_e32 v49, v50, v50
	v_lshlrev_b32_e32 v154, 16, v52
	v_and_b32_e32 v155, 0xffff0000, v52
	v_lshlrev_b32_e32 v52, 16, v58
	v_fmac_f32_e32 v49, v51, v51
	v_lshlrev_b32_e32 v156, 16, v53
	v_and_b32_e32 v157, 0xffff0000, v53
	v_and_b32_e32 v53, 0xffff0000, v58
	v_fmac_f32_e32 v49, v52, v52
	v_lshlrev_b32_e32 v158, 16, v54
	v_and_b32_e32 v159, 0xffff0000, v54
	v_lshlrev_b32_e32 v54, 16, v59
	v_fmac_f32_e32 v49, v53, v53
	v_lshlrev_b32_e32 v160, 16, v55
	v_and_b32_e32 v161, 0xffff0000, v55
	v_and_b32_e32 v55, 0xffff0000, v59
	v_fmac_f32_e32 v49, v54, v54
	v_fmac_f32_e32 v49, v55, v55
	ds_bpermute_b32 v48, v63, v49
	v_lshlrev_b32_e32 v162, 16, v86
	v_and_b32_e32 v163, 0xffff0000, v86
	v_lshlrev_b32_e32 v164, 16, v87
	v_and_b32_e32 v165, 0xffff0000, v87
	s_waitcnt lgkmcnt(0)
	v_add_f32_e32 v48, v49, v48
	ds_bpermute_b32 v49, v108, v48
	v_lshlrev_b32_e32 v166, 16, v88
	v_and_b32_e32 v167, 0xffff0000, v88
	v_lshlrev_b32_e32 v168, 16, v89
	v_and_b32_e32 v169, 0xffff0000, v89
	s_waitcnt lgkmcnt(0)
	v_add_f32_e32 v48, v48, v49
	ds_bpermute_b32 v49, v109, v48
	v_lshlrev_b32_e32 v170, 16, v90
	v_and_b32_e32 v171, 0xffff0000, v90
	v_lshlrev_b32_e32 v172, 16, v91
	v_and_b32_e32 v173, 0xffff0000, v91
	s_waitcnt lgkmcnt(0)
	v_add_f32_e32 v48, v48, v49
	ds_bpermute_b32 v49, v110, v48
	v_lshlrev_b32_e32 v174, 16, v92
	v_and_b32_e32 v175, 0xffff0000, v92
	v_lshlrev_b32_e32 v176, 16, v93
	v_and_b32_e32 v177, 0xffff0000, v93
	s_waitcnt lgkmcnt(0)
	v_add_f32_e32 v48, v48, v49
	ds_bpermute_b32 v49, v111, v48
	v_mul_f32_e32 v52, v171, v171
	v_fmac_f32_e32 v52, v170, v170
	v_fmac_f32_e32 v52, v172, v172
	v_fmac_f32_e32 v52, v173, v173
	s_waitcnt lgkmcnt(0)
	v_add_f32_e32 v54, v48, v49
	v_lshl_add_u64 v[48:49], s[20:21], 0, v[64:65]
	flat_load_dwordx4 v[86:89], v[48:49]
	flat_load_dwordx4 v[90:93], v[48:49] offset:16
	flat_load_dwordx4 v[114:117], v[48:49] offset:32
	flat_load_dwordx4 v[118:121], v[48:49] offset:48
	flat_load_dwordx4 v[122:125], v[48:49] offset:64
	flat_load_dwordx4 v[126:129], v[48:49] offset:80
	flat_load_dwordx4 v[130:133], v[48:49] offset:96
	flat_load_dwordx4 v[134:137], v[48:49] offset:112
	v_fmac_f32_e32 v52, v174, v174
	v_fmac_f32_e32 v52, v175, v175
	v_fmac_f32_e32 v52, v176, v176
	v_fmac_f32_e32 v52, v177, v177
	v_fmac_f32_e32 v52, v162, v162
	v_fmac_f32_e32 v52, v163, v163
	v_fmac_f32_e32 v52, v164, v164
	v_fmac_f32_e32 v52, v165, v165
	v_fmac_f32_e32 v52, v166, v166
	v_fmac_f32_e32 v52, v167, v167
	v_fmac_f32_e32 v52, v168, v168
	v_fmac_f32_e32 v52, v169, v169
	v_fmac_f32_e32 v52, v145, v145
	v_fmac_f32_e32 v52, v146, v146
	v_fmac_f32_e32 v52, v148, v148
	v_fmac_f32_e32 v52, v149, v149
	v_fmac_f32_e32 v52, v150, v150
	v_fmac_f32_e32 v52, v151, v151
	v_fmac_f32_e32 v52, v152, v152
	v_fmac_f32_e32 v52, v153, v153
	v_fmac_f32_e32 v52, v154, v154
	v_fmac_f32_e32 v52, v155, v155
	v_lshlrev_b32_e32 v99, 16, v41
	v_and_b32_e32 v103, 0xffff0000, v41
	v_fmac_f32_e32 v52, v156, v156
	v_lshlrev_b32_e32 v98, 16, v37
	v_and_b32_e32 v102, 0xffff0000, v37
	v_mov_b32_e32 v50, v103
	v_mov_b32_e32 v51, v99
	v_and_b32_e32 v105, 0xffff0000, v40
	v_and_b32_e32 v104, 0xffff0000, v36
	v_fmac_f32_e32 v52, v157, v157
	v_mov_b32_e32 v48, v102
	v_mov_b32_e32 v49, v98
	v_pk_mul_f32 v[50:51], v[50:51], v[50:51]
	v_lshlrev_b32_e32 v97, 16, v40
	v_lshlrev_b32_e32 v96, 16, v36
	v_pk_mul_f32 v[36:37], v[104:105], v[104:105]
	v_lshlrev_b32_e32 v95, 16, v39
	v_lshlrev_b32_e32 v94, 16, v35
	v_fmac_f32_e32 v52, v158, v158
	v_pk_fma_f32 v[48:49], v[48:49], v[48:49], v[50:51]
	v_pk_mul_f32 v[50:51], v[96:97], v[96:97]
	v_add_f32_e32 v40, v36, v37
	v_pk_mul_f32 v[36:37], v[94:95], v[94:95]
	v_and_b32_e32 v107, 0xffff0000, v39
	v_and_b32_e32 v106, 0xffff0000, v35
	v_fmac_f32_e32 v52, v159, v159
	v_add_f32_e32 v41, v50, v51
	v_add_f32_e32 v50, v36, v37
	v_pk_mul_f32 v[36:37], v[106:107], v[106:107]
	v_lshlrev_b32_e32 v139, 16, v38
	v_lshlrev_b32_e32 v138, 16, v34
	v_fmac_f32_e32 v52, v160, v160
	v_add_f32_e32 v39, v36, v37
	v_pk_mul_f32 v[36:37], v[138:139], v[138:139]
	v_fmac_f32_e32 v52, v161, v161
	v_add_f32_e32 v35, v36, v37
	v_and_b32_e32 v141, 0xffff0000, v38
	v_and_b32_e32 v140, 0xffff0000, v34
	v_add_f32_e32 v36, v35, v52
	v_pk_mul_f32 v[34:35], v[140:141], v[140:141]
	ds_bpermute_b32 v55, v112, v54
	v_add_f32_e32 v34, v34, v35
	v_add_f32_e32 v34, v34, v36
	v_add_f32_e32 v34, v50, v34
	v_add_f32_e32 v34, v39, v34
	v_add_f32_e32 v34, v41, v34
	v_add_f32_e32 v34, v40, v34
	v_add_f32_e32 v34, v49, v34
	v_add_f32_e32 v34, v48, v34
	ds_bpermute_b32 v35, v63, v34
	s_waitcnt lgkmcnt(0)
	v_add_f32_e32 v36, v54, v55
	v_fmamk_f32 v36, v36, 0x3b000000, v113
	v_rsq_f32_e32 v144, v36
	global_load_dwordx4 v[58:61], v[44:45], off offset:2112
	global_load_dwordx4 v[50:53], v[46:47], off offset:16
	v_add_f32_e32 v38, v34, v35
	ds_bpermute_b32 v39, v108, v38
	global_load_dwordx4 v[54:57], v[82:83], off
	global_load_dwordx4 v[46:49], v[82:83], off offset:64
	global_load_dwordx4 v[34:37], v[42:43], off offset:48
	s_waitcnt lgkmcnt(0)
	v_add_f32_e32 v38, v38, v39
	v_mul_f32_e32 v38, v144, v38
	v_mul_f32_e32 v38, v144, v38
	v_fmamk_f32 v38, v38, 0x3baaaaab, v113
	v_rsq_f32_e32 v178, v38
	global_load_dwordx4 v[38:41], v[42:43], off offset:32
	s_nop 0
	global_load_dwordx4 v[42:45], v[42:43], off offset:16
	v_mul_f32_e32 v144, v144, v178
	v_mul_f32_e32 v144, 0x3dd53b95, v144
	s_waitcnt vmcnt(0)
	v_mul_f32_e32 v86, v86, v144
	v_mul_f32_e32 v87, v87, v144
	v_mul_f32_e32 v88, v88, v144
	v_mul_f32_e32 v89, v89, v144
	v_mul_f32_e32 v86, v86, v170
	v_mul_f32_e32 v87, v87, v171
	v_mul_f32_e32 v88, v88, v172
	v_mul_f32_e32 v89, v89, v173
	v_mul_f32_e32 v90, v90, v144
	v_mul_f32_e32 v91, v91, v144
	v_mul_f32_e32 v92, v92, v144
	v_mul_f32_e32 v93, v93, v144
	v_mul_f32_e32 v90, v90, v174
	v_mul_f32_e32 v91, v91, v175
	v_mul_f32_e32 v92, v92, v176
	v_mul_f32_e32 v93, v93, v177
	v_mul_f32_e32 v114, v114, v144
	v_mul_f32_e32 v115, v115, v144
	v_mul_f32_e32 v116, v116, v144
	v_mul_f32_e32 v117, v117, v144
	v_mul_f32_e32 v118, v118, v144
	v_mul_f32_e32 v119, v119, v144
	v_mul_f32_e32 v120, v120, v144
	v_mul_f32_e32 v121, v121, v144
	v_cvt_pk_bf16_f32 v86, v86, v87
	v_cvt_pk_bf16_f32 v87, v88, v89
	v_cvt_pk_bf16_f32 v88, v90, v91
	v_cvt_pk_bf16_f32 v89, v92, v93
	v_mul_f32_e32 v114, v114, v162
	v_mul_f32_e32 v115, v115, v163
	v_mul_f32_e32 v116, v116, v164
	v_mul_f32_e32 v117, v117, v165
	v_mul_f32_e32 v118, v118, v166
	v_mul_f32_e32 v119, v119, v167
	v_mul_f32_e32 v120, v120, v168
	v_mul_f32_e32 v121, v121, v169
	v_mul_f32_e32 v122, v122, v144
	v_mul_f32_e32 v123, v123, v144
	v_mul_f32_e32 v124, v124, v144
	v_mul_f32_e32 v125, v125, v144
	v_mul_f32_e32 v126, v126, v144
	v_mul_f32_e32 v127, v127, v144
	v_mul_f32_e32 v128, v128, v144
	v_mul_f32_e32 v129, v129, v144
	global_store_dwordx4 v[84:85], v[86:89], off
	v_mul_f32_e32 v122, v122, v145
	v_mul_f32_e32 v123, v123, v146
	v_cvt_pk_bf16_f32 v86, v114, v115
	v_cvt_pk_bf16_f32 v87, v116, v117
	v_cvt_pk_bf16_f32 v88, v118, v119
	v_cvt_pk_bf16_f32 v89, v120, v121
	v_mul_f32_e32 v124, v124, v148
	v_mul_f32_e32 v125, v125, v149
	v_mul_f32_e32 v126, v126, v150
	v_mul_f32_e32 v127, v127, v151
	v_mul_f32_e32 v128, v128, v152
	v_mul_f32_e32 v129, v129, v153
	v_mul_f32_e32 v130, v130, v144
	v_mul_f32_e32 v131, v131, v144
	v_mul_f32_e32 v132, v132, v144
	v_mul_f32_e32 v133, v133, v144
	v_mul_f32_e32 v134, v134, v144
	v_mul_f32_e32 v135, v135, v144
	v_mul_f32_e32 v136, v136, v144
	v_mul_f32_e32 v137, v137, v144
	global_store_dwordx4 v[84:85], v[86:89], off offset:16
	v_mul_f32_e32 v130, v130, v154
	v_mul_f32_e32 v131, v131, v155
	v_cvt_pk_bf16_f32 v86, v122, v123
	v_cvt_pk_bf16_f32 v87, v124, v125
	v_cvt_pk_bf16_f32 v88, v126, v127
	v_cvt_pk_bf16_f32 v89, v128, v129
	v_mul_f32_e32 v132, v132, v156
	v_mul_f32_e32 v133, v133, v157
	v_mul_f32_e32 v134, v134, v158
	v_mul_f32_e32 v135, v135, v159
	v_mul_f32_e32 v136, v136, v160
	v_mul_f32_e32 v137, v137, v161
	global_store_dwordx4 v[84:85], v[86:89], off offset:32
	v_pk_mul_f32 v[92:93], v[144:145], v[138:139] op_sel_hi:[0,1]
	v_mov_b32_e32 v90, v10
	v_cvt_pk_bf16_f32 v86, v130, v131
	v_cvt_pk_bf16_f32 v87, v132, v133
	v_cvt_pk_bf16_f32 v88, v134, v135
	v_cvt_pk_bf16_f32 v89, v136, v137
	global_store_dwordx4 v[84:85], v[86:89], off offset:48
	flat_load_dwordx4 v[114:117], v[142:143] offset:512
	flat_load_dwordx4 v[118:121], v[142:143] offset:640
	flat_load_dwordx4 v[122:125], v[142:143] offset:528
	flat_load_dwordx4 v[126:129], v[142:143] offset:656
	v_mov_b32_e32 v91, v14
	v_pk_mul_f32 v[94:95], v[144:145], v[94:95] op_sel_hi:[0,1]
	v_mov_b32_e32 v88, v12
	v_mov_b32_e32 v89, v16
	v_pk_mul_f32 v[106:107], v[144:145], v[106:107] op_sel_hi:[0,1]
	v_pk_mul_f32 v[96:97], v[144:145], v[96:97] op_sel_hi:[0,1]
	v_mov_b32_e32 v86, v2
	v_mov_b32_e32 v87, v6
	v_pk_mul_f32 v[104:105], v[144:145], v[104:105] op_sel_hi:[0,1]
	v_pk_mul_f32 v[98:99], v[144:145], v[98:99] op_sel_hi:[0,1]
	v_mov_b32_e32 v84, v4
	v_mov_b32_e32 v85, v8
	v_pk_mul_f32 v[102:103], v[144:145], v[102:103] op_sel_hi:[0,1]
	s_waitcnt vmcnt(0) lgkmcnt(0)
	v_mov_b32_e32 v130, v114
	v_mov_b32_e32 v131, v118
	v_pk_mul_f32 v[130:131], v[92:93], v[130:131]
	v_mov_b32_e32 v118, v115
	v_pk_mul_f32 v[92:93], v[90:91], v[130:131]
	s_nop 0
	v_sub_f32_e32 v132, v92, v93
	v_mov_b32_e32 v92, v14
	v_mov_b32_e32 v93, v10
	v_pk_mul_f32 v[130:131], v[92:93], v[130:131]
	v_mov_b32_e32 v14, v11
	v_add_f32_e32 v133, v130, v131
	v_pk_mul_f32 v[130:131], v[144:145], v[140:141] op_sel_hi:[0,1]
	v_pk_mul_f32 v[114:115], v[130:131], v[118:119]
	v_mov_b32_e32 v10, v15
	v_pk_mul_f32 v[118:119], v[14:15], v[114:115]
	v_pk_mul_f32 v[114:115], v[10:11], v[114:115]
	v_sub_f32_e32 v118, v118, v119
	v_add_f32_e32 v119, v114, v115
	v_mov_b32_e32 v114, v116
	v_mov_b32_e32 v115, v120
	v_pk_mul_f32 v[114:115], v[94:95], v[114:115]
	v_mov_b32_e32 v120, v117
	v_pk_mul_f32 v[94:95], v[88:89], v[114:115]
	v_pk_mul_f32 v[106:107], v[106:107], v[120:121]
	v_sub_f32_e32 v116, v94, v95
	v_mov_b32_e32 v94, v16
	v_mov_b32_e32 v95, v12
	v_pk_mul_f32 v[114:115], v[94:95], v[114:115]
	v_mov_b32_e32 v16, v13
	v_mov_b32_e32 v12, v17
	v_add_f32_e32 v130, v114, v115
	v_pk_mul_f32 v[114:115], v[16:17], v[106:107]
	v_pk_mul_f32 v[106:107], v[12:13], v[106:107]
	v_sub_f32_e32 v114, v114, v115
	v_add_f32_e32 v115, v106, v107
	v_mov_b32_e32 v106, v122
	v_mov_b32_e32 v107, v126
	v_pk_mul_f32 v[106:107], v[96:97], v[106:107]
	v_mov_b32_e32 v126, v123
	v_pk_mul_f32 v[96:97], v[86:87], v[106:107]
	v_pk_mul_f32 v[104:105], v[104:105], v[126:127]
	v_sub_f32_e32 v117, v96, v97
	v_mov_b32_e32 v96, v6
	v_mov_b32_e32 v97, v2
	v_pk_mul_f32 v[106:107], v[96:97], v[106:107]
	v_mov_b32_e32 v6, v3
	v_mov_b32_e32 v2, v7
	v_add_f32_e32 v120, v106, v107
	v_pk_mul_f32 v[106:107], v[6:7], v[104:105]
	v_pk_mul_f32 v[104:105], v[2:3], v[104:105]
	v_sub_f32_e32 v106, v106, v107
	v_add_f32_e32 v107, v104, v105
	v_mov_b32_e32 v104, v124
	v_mov_b32_e32 v105, v128
	v_pk_mul_f32 v[104:105], v[98:99], v[104:105]
	v_mov_b32_e32 v128, v125
	v_pk_mul_f32 v[98:99], v[84:85], v[104:105]
	v_pk_mul_f32 v[102:103], v[102:103], v[128:129]
	v_sub_f32_e32 v121, v98, v99
	v_mov_b32_e32 v98, v8
	v_mov_b32_e32 v99, v4
	v_pk_mul_f32 v[104:105], v[98:99], v[104:105]
	v_mov_b32_e32 v8, v5
	v_add_f32_e32 v122, v104, v105
	v_pk_mul_f32 v[104:105], v[8:9], v[102:103]
	v_mov_b32_e32 v4, v9
	v_sub_f32_e32 v105, v104, v105
	v_pk_mul_f32 v[102:103], v[4:5], v[102:103]
	s_nop 0
	v_add_f32_e32 v123, v102, v103
	v_cvt_pk_bf16_f32 v102, v132, v118
	v_cvt_pk_bf16_f32 v103, v116, v114
	v_cvt_pk_bf16_f32 v104, v117, v106
	v_cvt_pk_bf16_f32 v105, v121, v105
	global_store_dwordx4 v[100:101], v[102:105], off
	s_nop 1
	v_cvt_pk_bf16_f32 v102, v133, v119
	v_cvt_pk_bf16_f32 v103, v130, v115
	v_cvt_pk_bf16_f32 v104, v120, v107
	v_cvt_pk_bf16_f32 v105, v122, v123
	global_store_dwordx4 v[100:101], v[102:105], off offset:64
	v_and_b32_e32 v146, 0xffff0000, v54
	v_lshlrev_b32_e32 v148, 16, v54
	v_mul_f32_e32 v185, v146, v146
	v_lshlrev_b32_e32 v145, 16, v55
	v_fmac_f32_e32 v185, v148, v148
	v_and_b32_e32 v144, 0xffff0000, v55
	v_fmac_f32_e32 v185, v145, v145
	v_lshlrev_b32_e32 v152, 16, v56
	v_fmac_f32_e32 v185, v144, v144
	v_and_b32_e32 v151, 0xffff0000, v56
	v_fmac_f32_e32 v185, v152, v152
	v_lshlrev_b32_e32 v150, 16, v57
	v_fmac_f32_e32 v185, v151, v151
	v_and_b32_e32 v149, 0xffff0000, v57
	v_fmac_f32_e32 v185, v150, v150
	v_lshlrev_b32_e32 v139, 16, v50
	v_fmac_f32_e32 v185, v149, v149
	v_and_b32_e32 v158, 0xffff0000, v30
	v_lshlrev_b32_e32 v156, 16, v31
	v_and_b32_e32 v155, 0xffff0000, v31
	v_lshlrev_b32_e32 v154, 16, v32
	v_and_b32_e32 v153, 0xffff0000, v32
	v_and_b32_e32 v106, 0xffff0000, v33
	v_lshlrev_b32_e32 v107, 16, v33
	v_and_b32_e32 v31, 0xffff0000, v58
	v_lshlrev_b32_e32 v33, 16, v59
	v_lshlrev_b32_e32 v32, 16, v58
	v_and_b32_e32 v138, 0xffff0000, v50
	v_fmac_f32_e32 v185, v139, v139
	v_lshlrev_b32_e32 v157, 16, v30
	v_and_b32_e32 v30, 0xffff0000, v26
	v_lshlrev_b32_e32 v101, 16, v27
	v_lshlrev_b32_e32 v100, 16, v26
	v_lshlrev_b32_e32 v103, 16, v28
	v_and_b32_e32 v102, 0xffff0000, v27
	v_lshlrev_b32_e32 v27, 16, v60
	v_lshlrev_b32_e32 v105, 16, v29
	v_and_b32_e32 v104, 0xffff0000, v28
	v_and_b32_e32 v58, 0xffff0000, v60
	v_and_b32_e32 v60, 0xffff0000, v29
	v_lshlrev_b32_e32 v137, 16, v51
	v_lshlrev_b32_e32 v115, 16, v46
	v_and_b32_e32 v114, 0xffff0000, v46
	v_lshlrev_b32_e32 v57, 16, v47
	v_and_b32_e32 v56, 0xffff0000, v47
	v_lshlrev_b32_e32 v47, 16, v40
	v_and_b32_e32 v46, 0xffff0000, v40
	v_and_b32_e32 v28, 0xffff0000, v41
	v_lshlrev_b32_e32 v29, 16, v41
	v_mul_f32_e32 v184, v158, v158
	v_pk_mul_f32 v[40:41], v[106:107], v[106:107]
	v_mul_f32_e32 v106, v31, v31
	v_pk_mul_f32 v[166:167], v[32:33], v[32:33]
	v_fmac_f32_e32 v185, v138, v138
	v_and_b32_e32 v26, 0xffff0000, v59
	v_and_b32_e32 v136, 0xffff0000, v51
	v_lshlrev_b32_e32 v123, 16, v18
	v_and_b32_e32 v122, 0xffff0000, v18
	v_lshlrev_b32_e32 v121, 16, v19
	v_and_b32_e32 v120, 0xffff0000, v19
	v_lshlrev_b32_e32 v127, 16, v20
	v_and_b32_e32 v126, 0xffff0000, v20
	v_lshlrev_b32_e32 v125, 16, v21
	v_and_b32_e32 v124, 0xffff0000, v21
	v_and_b32_e32 v18, 0xffff0000, v34
	v_lshlrev_b32_e32 v19, 16, v34
	v_and_b32_e32 v20, 0xffff0000, v35
	v_lshlrev_b32_e32 v21, 16, v35
	v_lshl_add_u64 v[34:35], s[18:19], 0, v[80:81]
	v_fmac_f32_e32 v184, v157, v157
	v_pk_fma_f32 v[106:107], v[30:31], v[30:31], v[106:107] op_sel_hi:[1,1,0]
	v_pk_fma_f32 v[166:167], v[100:101], v[100:101], v[166:167]
	v_fmac_f32_e32 v185, v137, v137
	v_lshlrev_b32_e32 v143, 16, v52
	v_pk_mul_f32 v[168:169], v[26:27], v[26:27]
	v_mov_b32_e32 v158, v190
	v_mov_b32_e32 v159, v191
	v_mov_b32_e32 v160, v192
	v_mov_b32_e32 v161, v193
	v_mov_b32_e32 v162, v194
	v_mov_b32_e32 v163, v195
	v_mov_b32_e32 v164, v196
	v_mov_b32_e32 v165, v197
	v_fmac_f32_e32 v184, v156, v156
	v_pk_add_f32 v[106:107], v[166:167], v[106:107]
	v_fmac_f32_e32 v185, v136, v136
	v_lshlrev_b32_e32 v59, 16, v61
	v_and_b32_e32 v142, 0xffff0000, v52
	v_pk_fma_f32 v[168:169], v[102:103], v[102:103], v[168:169]
	v_fmac_f32_e32 v184, v155, v155
	v_pk_add_f32 v[106:107], v[166:167], v[106:107] op_sel:[1,0] op_sel_hi:[0,1]
	v_fmac_f32_e32 v185, v143, v143
	v_lshlrev_b32_e32 v141, 16, v53
	v_pk_mul_f32 v[170:171], v[58:59], v[58:59]
	v_fmac_f32_e32 v184, v154, v154
	v_pk_add_f32 v[106:107], v[168:169], v[106:107]
	v_fmac_f32_e32 v185, v142, v142
	v_and_b32_e32 v140, 0xffff0000, v53
	v_pk_fma_f32 v[170:171], v[104:105], v[104:105], v[170:171]
	v_fmac_f32_e32 v184, v153, v153
	v_pk_add_f32 v[106:107], v[168:169], v[106:107] op_sel:[1,0] op_sel_hi:[0,1]
	v_fmac_f32_e32 v185, v141, v141
	v_lshlrev_b32_e32 v131, 16, v22
	v_add_f32_e32 v41, v41, v184
	v_pk_add_f32 v[106:107], v[170:171], v[106:107]
	v_fmac_f32_e32 v185, v140, v140
	v_and_b32_e32 v130, 0xffff0000, v22
	v_add_f32_e32 v153, v40, v41
	v_pk_add_f32 v[40:41], v[170:171], v[106:107] op_sel:[1,0] op_sel_hi:[0,1]
	v_fmac_f32_e32 v185, v131, v131
	v_lshlrev_b32_e32 v129, 16, v23
	ds_bpermute_b32 v41, v63, v153
	v_fmac_f32_e32 v185, v130, v130
	v_and_b32_e32 v128, 0xffff0000, v23
	v_fmac_f32_e32 v185, v129, v129
	v_lshlrev_b32_e32 v135, 16, v24
	v_fmac_f32_e32 v185, v128, v128
	v_and_b32_e32 v134, 0xffff0000, v24
	v_fmac_f32_e32 v185, v135, v135
	v_lshlrev_b32_e32 v133, 16, v25
	v_fmac_f32_e32 v185, v134, v134
	v_and_b32_e32 v132, 0xffff0000, v25
	s_waitcnt lgkmcnt(0)
	v_add_f32_e32 v41, v153, v41
	v_fmac_f32_e32 v185, v133, v133
	ds_bpermute_b32 v106, v108, v41
	v_fmac_f32_e32 v185, v132, v132
	v_fmac_f32_e32 v185, v123, v123
	v_fmac_f32_e32 v185, v122, v122
	v_fmac_f32_e32 v185, v121, v121
	v_fmac_f32_e32 v185, v120, v120
	s_waitcnt lgkmcnt(0)
	v_add_f32_e32 v41, v41, v106
	v_fmac_f32_e32 v185, v127, v127
	ds_bpermute_b32 v106, v109, v41
	v_fmac_f32_e32 v185, v126, v126
	v_fmac_f32_e32 v185, v125, v125
	v_fmac_f32_e32 v185, v124, v124
	v_fmac_f32_e32 v185, v115, v115
	v_fmac_f32_e32 v185, v114, v114
	s_waitcnt lgkmcnt(0)
	v_add_f32_e32 v41, v41, v106
	v_fmac_f32_e32 v185, v57, v57
	v_lshlrev_b32_e32 v119, 16, v48
	ds_bpermute_b32 v106, v110, v41
	v_fmac_f32_e32 v185, v56, v56
	v_and_b32_e32 v118, 0xffff0000, v48
	v_fmac_f32_e32 v185, v119, v119
	v_lshlrev_b32_e32 v117, 16, v49
	v_fmac_f32_e32 v185, v118, v118
	v_and_b32_e32 v116, 0xffff0000, v49
	v_fmac_f32_e32 v185, v117, v117
	v_lshlrev_b32_e32 v51, 16, v42
	v_fmac_f32_e32 v185, v116, v116
	v_and_b32_e32 v50, 0xffff0000, v42
	s_waitcnt lgkmcnt(0)
	v_add_f32_e32 v41, v41, v106
	v_fmac_f32_e32 v185, v51, v51
	v_lshlrev_b32_e32 v49, 16, v43
	ds_bpermute_b32 v106, v111, v41
	v_fmac_f32_e32 v185, v50, v50
	v_and_b32_e32 v48, 0xffff0000, v43
	v_fmac_f32_e32 v185, v49, v49
	v_lshlrev_b32_e32 v55, 16, v44
	v_fmac_f32_e32 v185, v48, v48
	v_and_b32_e32 v54, 0xffff0000, v44
	v_fmac_f32_e32 v185, v55, v55
	v_lshlrev_b32_e32 v53, 16, v45
	v_fmac_f32_e32 v185, v54, v54
	v_and_b32_e32 v52, 0xffff0000, v45
	s_waitcnt lgkmcnt(0)
	v_add_f32_e32 v41, v41, v106
	v_fmac_f32_e32 v185, v53, v53
	v_lshlrev_b32_e32 v45, 16, v38
	ds_bpermute_b32 v106, v112, v41
	v_fmac_f32_e32 v185, v52, v52
	v_and_b32_e32 v44, 0xffff0000, v38
	v_fmac_f32_e32 v185, v45, v45
	v_lshlrev_b32_e32 v43, 16, v39
	v_fmac_f32_e32 v185, v44, v44
	v_and_b32_e32 v42, 0xffff0000, v39
	v_fmac_f32_e32 v185, v43, v43
	v_fmac_f32_e32 v185, v42, v42
	s_waitcnt lgkmcnt(0)
	v_add_f32_e32 v41, v41, v106
	v_fmac_f32_e32 v185, v47, v47
	v_pk_mul_f32 v[172:173], v[28:29], v[28:29]
	v_fmamk_f32 v41, v41, 0x3b000000, v113
	v_fmac_f32_e32 v185, v46, v46
	v_rsq_f32_e32 v153, v41
	v_add_f32_e32 v41, v173, v185
	v_pk_mul_f32 v[174:175], v[18:19], v[18:19]
	v_add_f32_e32 v41, v172, v41
	v_add_f32_e32 v41, v175, v41
	v_pk_mul_f32 v[176:177], v[20:21], v[20:21]
	v_add_f32_e32 v41, v174, v41
	v_and_b32_e32 v22, 0xffff0000, v36
	v_lshlrev_b32_e32 v23, 16, v36
	v_add_f32_e32 v41, v177, v41
	v_pk_mul_f32 v[178:179], v[22:23], v[22:23]
	v_add_f32_e32 v41, v176, v41
	v_and_b32_e32 v24, 0xffff0000, v37
	v_lshlrev_b32_e32 v25, 16, v37
	v_add_f32_e32 v41, v179, v41
	v_and_b32_e32 v61, 0xffff0000, v61
	v_pk_mul_f32 v[180:181], v[24:25], v[24:25]
	v_add_f32_e32 v41, v178, v41
	v_mul_f32_e32 v182, v61, v61
	v_add_f32_e32 v41, v181, v41
	v_pk_fma_f32 v[182:183], v[60:61], v[60:61], v[182:183] op_sel_hi:[1,1,0]
	v_add_f32_e32 v41, v180, v41
	v_cndmask_b32_e64 v183, 0, v41, s[0:1]
	ds_bpermute_b32 v106, v63, v183
	s_waitcnt vmcnt(0)
	v_cndmask_b32_e64 v155, v159, 1.0, s[4:5]
	v_cndmask_b32_e64 v156, v158, 1.0, s[4:5]
	v_cndmask_b32_e64 v159, v163, 1.0, s[4:5]
	v_cndmask_b32_e64 v154, v160, 1.0, s[4:5]
	s_waitcnt lgkmcnt(0)
	v_mov_b32_e32 v41, v106
	v_pk_add_f32 v[40:41], v[182:183], v[40:41]
	ds_bpermute_b32 v106, v63, v40
	ds_bpermute_b32 v107, v108, v41
	v_cndmask_b32_e64 v157, v165, 1.0, s[4:5]
	v_cndmask_b32_e64 v158, v164, 1.0, s[4:5]
	v_cndmask_b32_e64 v160, v162, 1.0, s[4:5]
	v_lshl_add_u64 v[36:37], s[18:19], 0, v[78:79]
	s_waitcnt lgkmcnt(0)
	v_pk_add_f32 v[40:41], v[40:41], v[106:107]
	ds_bpermute_b32 v106, v108, v40
	v_mul_f32_e32 v41, v41, v153
	v_cndmask_b32_e64 v107, v161, 1.0, s[4:5]
	v_lshl_add_u64 v[38:39], s[96:97], 0, v[76:77]
	s_add_i32 s31, s31, s46
	s_waitcnt lgkmcnt(0)
	v_add_f32_e32 v40, v40, v106
	v_fmac_f32_e32 v40, v153, v41
	v_fmamk_f32 v40, v40, 0x3baaaaab, v113
	v_rsq_f32_e32 v40, v40
	s_add_i32 s26, s26, s27
	v_add_co_u32_e32 v38, vcc, s28, v38
	v_mul_f32_e32 v41, v153, v40
	v_cndmask_b32_e64 v41, v153, v41, s[0:1]
	v_mul_f32_e32 v106, v156, v41
	v_mul_f32_e32 v156, v159, v41
	v_mul_f32_e32 v153, v160, v41
	v_mul_f32_e32 v155, v155, v41
	v_mul_f32_e32 v154, v154, v41
	v_mul_f32_e32 v158, v158, v41
	v_mul_f32_e32 v107, v107, v41
	v_mul_f32_e32 v157, v157, v41
	v_mul_f32_e32 v151, v156, v151
	v_mul_f32_e32 v106, v106, v148
	v_mul_f32_e32 v152, v153, v152
	v_mul_f32_e32 v146, v155, v146
	v_mul_f32_e32 v145, v154, v145
	v_mul_f32_e32 v153, v158, v150
	v_mul_f32_e32 v107, v107, v144
	v_mul_f32_e32 v144, v157, v149
	v_cvt_pk_bf16_f32 v148, v106, v146
	v_cvt_pk_bf16_f32 v149, v145, v107
	v_cvt_pk_bf16_f32 v150, v152, v151
	v_cvt_pk_bf16_f32 v151, v153, v144
	global_store_dwordx4 v[82:83], v[148:151], off
	s_nop 1
	v_mov_b32_e32 v148, v198
	v_mov_b32_e32 v149, v199
	v_mov_b32_e32 v150, v200
	v_mov_b32_e32 v151, v201
	s_nop 0
	v_mov_b32_e32 v152, v202
	v_mov_b32_e32 v153, v203
	v_mov_b32_e32 v154, v204
	v_mov_b32_e32 v155, v205
	v_lshl_add_u64 v[66:67], v[66:67], 0, s[6:7]
	v_lshl_add_u64 v[68:69], v[68:69], 0, s[8:9]
	v_lshl_add_u64 v[70:71], v[70:71], 0, s[8:9]
	v_lshl_add_u64 v[72:73], v[72:73], 0, s[10:11]
	v_lshl_add_u64 v[74:75], v[74:75], 0, s[10:11]
	v_lshl_add_u64 v[76:77], v[76:77], 0, s[10:11]
	v_addc_co_u32_e32 v39, vcc, 0, v39, vcc
	s_cmp_lt_i32 s31, 0x8000
	s_waitcnt lgkmcnt(0)
	v_cndmask_b32_e64 v144, v149, 1.0, s[4:5]
	v_cndmask_b32_e64 v145, v148, 1.0, s[4:5]
	v_cndmask_b32_e64 v106, v151, 1.0, s[4:5]
	v_cndmask_b32_e64 v107, v150, 1.0, s[4:5]
	v_cndmask_b32_e64 v146, v155, 1.0, s[4:5]
	v_cndmask_b32_e64 v148, v154, 1.0, s[4:5]
	v_cndmask_b32_e64 v149, v153, 1.0, s[4:5]
	v_cndmask_b32_e64 v150, v152, 1.0, s[4:5]
	v_mul_f32_e32 v145, v145, v41
	v_mul_f32_e32 v144, v144, v41
	v_mul_f32_e32 v150, v41, v150
	v_mul_f32_e32 v149, v41, v149
	v_mul_f32_e32 v107, v107, v41
	v_mul_f32_e32 v148, v41, v148
	v_mul_f32_e32 v106, v106, v41
	v_mul_f32_e32 v146, v41, v146
	v_mul_f32_e32 v139, v145, v139
	v_mul_f32_e32 v138, v144, v138
	v_mul_f32_e32 v143, v150, v143
	v_mul_f32_e32 v142, v149, v142
	v_mul_f32_e32 v107, v107, v137
	v_mul_f32_e32 v141, v148, v141
	v_mul_f32_e32 v106, v106, v136
	v_mul_f32_e32 v140, v146, v140
	v_cvt_pk_bf16_f32 v136, v139, v138
	v_cvt_pk_bf16_f32 v137, v107, v106
	v_cvt_pk_bf16_f32 v138, v143, v142
	v_cvt_pk_bf16_f32 v139, v141, v140
	global_store_dwordx4 v[82:83], v[136:139], off offset:16
	s_nop 1
	v_mov_b32_e32 v136, v206
	v_mov_b32_e32 v137, v207
	v_mov_b32_e32 v138, v208
	v_mov_b32_e32 v139, v209
	s_nop 0
	v_mov_b32_e32 v140, v210
	v_mov_b32_e32 v141, v211
	v_mov_b32_e32 v142, v212
	v_mov_b32_e32 v143, v213
	s_waitcnt lgkmcnt(0)
	v_cndmask_b32_e64 v137, v137, 1.0, s[4:5]
	v_cndmask_b32_e64 v136, v136, 1.0, s[4:5]
	v_cndmask_b32_e64 v106, v139, 1.0, s[4:5]
	v_cndmask_b32_e64 v107, v138, 1.0, s[4:5]
	v_cndmask_b32_e64 v138, v143, 1.0, s[4:5]
	v_cndmask_b32_e64 v139, v142, 1.0, s[4:5]
	v_cndmask_b32_e64 v141, v141, 1.0, s[4:5]
	v_cndmask_b32_e64 v140, v140, 1.0, s[4:5]
	v_mul_f32_e32 v136, v41, v136
	v_mul_f32_e32 v137, v41, v137
	v_mul_f32_e32 v140, v41, v140
	v_mul_f32_e32 v141, v41, v141
	v_mul_f32_e32 v107, v41, v107
	v_mul_f32_e32 v139, v41, v139
	v_mul_f32_e32 v106, v41, v106
	v_mul_f32_e32 v138, v41, v138
	v_mul_f32_e32 v131, v136, v131
	v_mul_f32_e32 v130, v137, v130
	v_mul_f32_e32 v135, v140, v135
	v_mul_f32_e32 v134, v141, v134
	v_mul_f32_e32 v107, v107, v129
	v_mul_f32_e32 v133, v139, v133
	v_mul_f32_e32 v106, v106, v128
	v_mul_f32_e32 v132, v138, v132
	v_cvt_pk_bf16_f32 v128, v131, v130
	v_cvt_pk_bf16_f32 v129, v107, v106
	v_cvt_pk_bf16_f32 v130, v135, v134
	v_cvt_pk_bf16_f32 v131, v133, v132
	global_store_dwordx4 v[82:83], v[128:131], off offset:32
	s_nop 1
	v_mov_b32_e32 v128, v214
	v_mov_b32_e32 v129, v215
	v_mov_b32_e32 v130, v216
	v_mov_b32_e32 v131, v217
	s_nop 0
	v_mov_b32_e32 v132, v218
	v_mov_b32_e32 v133, v219
	v_mov_b32_e32 v134, v220
	v_mov_b32_e32 v135, v221
	s_waitcnt lgkmcnt(0)
	v_cndmask_b32_e64 v129, v129, 1.0, s[4:5]
	v_cndmask_b32_e64 v128, v128, 1.0, s[4:5]
	v_cndmask_b32_e64 v106, v131, 1.0, s[4:5]
	v_cndmask_b32_e64 v107, v130, 1.0, s[4:5]
	v_cndmask_b32_e64 v130, v135, 1.0, s[4:5]
	v_cndmask_b32_e64 v131, v134, 1.0, s[4:5]
	v_cndmask_b32_e64 v133, v133, 1.0, s[4:5]
	v_cndmask_b32_e64 v132, v132, 1.0, s[4:5]
	v_mul_f32_e32 v128, v41, v128
	v_mul_f32_e32 v129, v41, v129
	v_mul_f32_e32 v132, v41, v132
	v_mul_f32_e32 v133, v41, v133
	v_mul_f32_e32 v107, v41, v107
	v_mul_f32_e32 v131, v41, v131
	v_mul_f32_e32 v106, v41, v106
	v_mul_f32_e32 v130, v41, v130
	v_mul_f32_e32 v123, v128, v123
	v_mul_f32_e32 v122, v129, v122
	v_mul_f32_e32 v127, v132, v127
	v_mul_f32_e32 v126, v133, v126
	v_mul_f32_e32 v107, v107, v121
	v_mul_f32_e32 v125, v131, v125
	v_mul_f32_e32 v106, v106, v120
	v_mul_f32_e32 v124, v130, v124
	v_cvt_pk_bf16_f32 v120, v123, v122
	v_cvt_pk_bf16_f32 v121, v107, v106
	v_cvt_pk_bf16_f32 v122, v127, v126
	v_cvt_pk_bf16_f32 v123, v125, v124
	global_store_dwordx4 v[82:83], v[120:123], off offset:48
	s_nop 1
	v_mov_b32_e32 v120, v222
	v_mov_b32_e32 v121, v223
	v_mov_b32_e32 v122, v224
	v_mov_b32_e32 v123, v225
	s_nop 0
	v_mov_b32_e32 v124, v226
	v_mov_b32_e32 v125, v227
	v_mov_b32_e32 v126, v228
	v_mov_b32_e32 v127, v229
	s_waitcnt lgkmcnt(0)
	v_cndmask_b32_e64 v121, v121, 1.0, s[4:5]
	v_cndmask_b32_e64 v120, v120, 1.0, s[4:5]
	v_cndmask_b32_e64 v106, v123, 1.0, s[4:5]
	v_cndmask_b32_e64 v107, v122, 1.0, s[4:5]
	v_cndmask_b32_e64 v122, v127, 1.0, s[4:5]
	v_cndmask_b32_e64 v123, v126, 1.0, s[4:5]
	v_cndmask_b32_e64 v125, v125, 1.0, s[4:5]
	v_cndmask_b32_e64 v124, v124, 1.0, s[4:5]
	v_mul_f32_e32 v120, v41, v120
	v_mul_f32_e32 v121, v41, v121
	v_mul_f32_e32 v124, v41, v124
	v_mul_f32_e32 v125, v41, v125
	v_mul_f32_e32 v107, v41, v107
	v_mul_f32_e32 v123, v41, v123
	v_mul_f32_e32 v106, v41, v106
	v_mul_f32_e32 v122, v41, v122
	v_mul_f32_e32 v115, v120, v115
	v_mul_f32_e32 v114, v121, v114
	v_mul_f32_e32 v119, v124, v119
	v_mul_f32_e32 v118, v125, v118
	v_mul_f32_e32 v57, v107, v57
	v_mul_f32_e32 v107, v123, v117
	v_mul_f32_e32 v56, v106, v56
	v_mul_f32_e32 v106, v122, v116
	v_cvt_pk_bf16_f32 v114, v115, v114
	v_cvt_pk_bf16_f32 v115, v57, v56
	v_cvt_pk_bf16_f32 v116, v119, v118
	v_cvt_pk_bf16_f32 v117, v107, v106
	global_store_dwordx4 v[82:83], v[114:117], off offset:64
	s_nop 1
	v_mov_b32_e32 v114, v230
	v_mov_b32_e32 v115, v231
	v_mov_b32_e32 v116, v232
	v_mov_b32_e32 v117, v233
	s_nop 0
	v_mov_b32_e32 v118, v234
	v_mov_b32_e32 v119, v235
	v_mov_b32_e32 v120, v236
	v_mov_b32_e32 v121, v237
	s_waitcnt lgkmcnt(0)
	v_cndmask_b32_e64 v57, v116, 1.0, s[4:5]
	v_cndmask_b32_e64 v106, v115, 1.0, s[4:5]
	v_cndmask_b32_e64 v107, v114, 1.0, s[4:5]
	v_cndmask_b32_e64 v56, v117, 1.0, s[4:5]
	v_cndmask_b32_e64 v114, v121, 1.0, s[4:5]
	v_cndmask_b32_e64 v115, v120, 1.0, s[4:5]
	v_cndmask_b32_e64 v116, v119, 1.0, s[4:5]
	v_cndmask_b32_e64 v117, v118, 1.0, s[4:5]
	v_mul_f32_e32 v107, v41, v107
	v_mul_f32_e32 v106, v41, v106
	v_mul_f32_e32 v57, v41, v57
	v_mul_f32_e32 v117, v41, v117
	v_mul_f32_e32 v116, v41, v116
	v_mul_f32_e32 v115, v41, v115
	v_mul_f32_e32 v56, v41, v56
	v_mul_f32_e32 v114, v41, v114
	v_mul_f32_e32 v51, v107, v51
	v_mul_f32_e32 v50, v106, v50
	v_mul_f32_e32 v49, v57, v49
	v_mul_f32_e32 v55, v117, v55
	v_mul_f32_e32 v54, v116, v54
	v_mul_f32_e32 v53, v115, v53
	v_mul_f32_e32 v56, v56, v48
	v_mul_f32_e32 v52, v114, v52
	v_cvt_pk_bf16_f32 v48, v51, v50
	v_cvt_pk_bf16_f32 v49, v49, v56
	v_cvt_pk_bf16_f32 v50, v55, v54
	v_cvt_pk_bf16_f32 v51, v53, v52
	global_store_dwordx4 v[82:83], v[48:51], off offset:80
	s_nop 1
	v_mov_b32_e32 v48, v238
	v_mov_b32_e32 v49, v239
	v_mov_b32_e32 v50, v240
	v_mov_b32_e32 v51, v241
	s_nop 0
	v_mov_b32_e32 v52, v242
	v_mov_b32_e32 v53, v243
	v_mov_b32_e32 v54, v244
	v_mov_b32_e32 v55, v245
	s_waitcnt lgkmcnt(0)
	v_cndmask_b32_e64 v50, v50, 1.0, s[4:5]
	v_cndmask_b32_e64 v49, v49, 1.0, s[4:5]
	v_cndmask_b32_e64 v48, v48, 1.0, s[4:5]
	v_cndmask_b32_e64 v51, v51, 1.0, s[4:5]
	v_cndmask_b32_e64 v55, v55, 1.0, s[4:5]
	v_cndmask_b32_e64 v54, v54, 1.0, s[4:5]
	v_cndmask_b32_e64 v53, v53, 1.0, s[4:5]
	v_cndmask_b32_e64 v52, v52, 1.0, s[4:5]
	v_mul_f32_e32 v48, v41, v48
	v_mul_f32_e32 v49, v41, v49
	v_mul_f32_e32 v50, v41, v50
	v_mul_f32_e32 v52, v41, v52
	v_mul_f32_e32 v53, v41, v53
	v_mul_f32_e32 v54, v41, v54
	v_mul_f32_e32 v51, v41, v51
	v_mul_f32_e32 v55, v41, v55
	v_mul_f32_e32 v45, v48, v45
	v_mul_f32_e32 v44, v49, v44
	v_mul_f32_e32 v43, v50, v43
	v_mul_f32_e32 v47, v52, v47
	v_mul_f32_e32 v46, v53, v46
	v_mul_f32_e32 v29, v54, v29
	v_mul_f32_e32 v48, v51, v42
	v_mul_f32_e32 v28, v55, v28
	v_cvt_pk_bf16_f32 v42, v45, v44
	v_cvt_pk_bf16_f32 v43, v43, v48
	v_cvt_pk_bf16_f32 v44, v47, v46
	v_cvt_pk_bf16_f32 v45, v29, v28
	global_store_dwordx4 v[82:83], v[42:45], off offset:96
	s_nop 1
	v_mov_b32_e32 v42, v246
	v_mov_b32_e32 v43, v247
	v_mov_b32_e32 v44, v248
	v_mov_b32_e32 v45, v249
	s_nop 0
	v_mov_b32_e32 v46, v250
	v_mov_b32_e32 v47, v251
	v_mov_b32_e32 v48, v252
	v_mov_b32_e32 v49, v253
	s_waitcnt lgkmcnt(0)
	v_cndmask_b32_e64 v28, v45, 1.0, s[4:5]
	v_cndmask_b32_e64 v29, v44, 1.0, s[4:5]
	v_cndmask_b32_e64 v34, v43, 1.0, s[4:5]
	v_cndmask_b32_e64 v35, v42, 1.0, s[4:5]
	v_cndmask_b32_e64 v42, v49, 1.0, s[4:5]
	v_cndmask_b32_e64 v43, v48, 1.0, s[4:5]
	v_cndmask_b32_e64 v44, v47, 1.0, s[4:5]
	v_cndmask_b32_e64 v45, v46, 1.0, s[4:5]
	v_mul_f32_e32 v35, v41, v35
	v_mul_f32_e32 v34, v41, v34
	v_mul_f32_e32 v29, v41, v29
	v_mul_f32_e32 v28, v41, v28
	v_mul_f32_e32 v45, v41, v45
	v_mul_f32_e32 v44, v41, v44
	v_mul_f32_e32 v43, v41, v43
	v_mul_f32_e32 v41, v41, v42
	v_mul_f32_e32 v19, v35, v19
	v_mul_f32_e32 v18, v34, v18
	v_mul_f32_e32 v21, v29, v21
	v_mul_f32_e32 v20, v28, v20
	v_mul_f32_e32 v23, v45, v23
	v_mul_f32_e32 v22, v44, v22
	v_mul_f32_e32 v25, v43, v25
	v_mul_f32_e32 v24, v41, v24
	v_cvt_pk_bf16_f32 v18, v19, v18
	v_cvt_pk_bf16_f32 v19, v21, v20
	v_cvt_pk_bf16_f32 v20, v23, v22
	v_cvt_pk_bf16_f32 v21, v25, v24
	global_store_dwordx4 v[82:83], v[18:21], off offset:112
	flat_load_dwordx4 v[18:21], v[36:37] offset:512
	s_nop 0
	flat_load_dwordx4 v[22:25], v[36:37] offset:640
	flat_load_dwordx4 v[42:45], v[36:37] offset:528
	s_nop 0
	flat_load_dwordx4 v[34:37], v[36:37] offset:656
	v_mov_b32_e32 v28, v100
	v_mov_b32_e32 v29, v32
	v_mov_b32_e32 v32, v101
	v_mov_b32_e32 v46, v102
	v_mov_b32_e32 v47, v26
	v_mov_b32_e32 v26, v103
	v_mov_b32_e32 v48, v104
	v_mov_b32_e32 v49, v58
	v_mov_b32_e32 v58, v105
	v_pk_mul_f32 v[28:29], v[40:41], v[28:29] op_sel_hi:[0,1]
	v_pk_mul_f32 v[30:31], v[40:41], v[30:31] op_sel_hi:[0,1]
	v_pk_mul_f32 v[32:33], v[40:41], v[32:33] op_sel_hi:[0,1]
	v_pk_mul_f32 v[46:47], v[40:41], v[46:47] op_sel_hi:[0,1]
	v_pk_mul_f32 v[26:27], v[40:41], v[26:27] op_sel_hi:[0,1]
	v_pk_mul_f32 v[48:49], v[40:41], v[48:49] op_sel_hi:[0,1]
	v_pk_mul_f32 v[50:51], v[40:41], v[58:59] op_sel_hi:[0,1]
	v_pk_mul_f32 v[40:41], v[40:41], v[60:61] op_sel_hi:[0,1]
	s_waitcnt vmcnt(0) lgkmcnt(0)
	v_mov_b32_e32 v52, v18
	v_mov_b32_e32 v53, v22
	v_mov_b32_e32 v22, v19
	v_mov_b32_e32 v18, v20
	v_mov_b32_e32 v19, v24
	v_mov_b32_e32 v24, v21
	v_mov_b32_e32 v20, v42
	v_mov_b32_e32 v21, v34
	v_mov_b32_e32 v34, v43
	v_mov_b32_e32 v42, v44
	v_mov_b32_e32 v43, v36
	v_mov_b32_e32 v36, v45
	v_pk_mul_f32 v[28:29], v[28:29], v[52:53]
	v_pk_mul_f32 v[22:23], v[30:31], v[22:23]
	v_pk_mul_f32 v[18:19], v[32:33], v[18:19]
	v_pk_mul_f32 v[24:25], v[46:47], v[24:25]
	v_pk_mul_f32 v[20:21], v[26:27], v[20:21]
	v_pk_mul_f32 v[26:27], v[48:49], v[34:35]
	v_pk_mul_f32 v[30:31], v[50:51], v[42:43]
	v_pk_mul_f32 v[32:33], v[40:41], v[36:37]
	v_pk_mul_f32 v[34:35], v[90:91], v[28:29]
	v_pk_mul_f32 v[14:15], v[14:15], v[22:23]
	v_pk_mul_f32 v[10:11], v[10:11], v[22:23]
	v_pk_mul_f32 v[22:23], v[88:89], v[18:19]
	v_pk_mul_f32 v[18:19], v[94:95], v[18:19]
	v_pk_mul_f32 v[16:17], v[16:17], v[24:25]
	v_pk_mul_f32 v[12:13], v[12:13], v[24:25]
	v_pk_mul_f32 v[24:25], v[86:87], v[20:21]
	v_pk_mul_f32 v[6:7], v[6:7], v[26:27]
	v_pk_mul_f32 v[2:3], v[2:3], v[26:27]
	v_pk_mul_f32 v[26:27], v[84:85], v[30:31]
	v_pk_mul_f32 v[8:9], v[8:9], v[32:33]
	v_pk_mul_f32 v[4:5], v[4:5], v[32:33]
	v_pk_mul_f32 v[28:29], v[92:93], v[28:29]
	v_pk_mul_f32 v[20:21], v[96:97], v[20:21]
	v_pk_mul_f32 v[30:31], v[98:99], v[30:31]
	v_sub_f32_e32 v32, v34, v35
	v_sub_f32_e32 v14, v14, v15
	v_add_f32_e32 v10, v10, v11
	v_sub_f32_e32 v11, v22, v23
	v_add_f32_e32 v15, v18, v19
	v_sub_f32_e32 v16, v16, v17
	v_add_f32_e32 v12, v12, v13
	v_sub_f32_e32 v13, v24, v25
	v_sub_f32_e32 v6, v6, v7
	v_add_f32_e32 v7, v2, v3
	v_sub_f32_e32 v18, v26, v27
	v_sub_f32_e32 v8, v8, v9
	v_add_f32_e32 v9, v4, v5
	v_cvt_pk_bf16_f32 v2, v32, v14
	v_cvt_pk_bf16_f32 v3, v11, v16
	v_cvt_pk_bf16_f32 v4, v13, v6
	v_cvt_pk_bf16_f32 v5, v18, v8
	v_add_f32_e32 v28, v28, v29
	v_add_f32_e32 v17, v20, v21
	v_add_f32_e32 v19, v30, v31
	global_store_dwordx4 v[38:39], v[2:5], off
	s_nop 1
	v_cvt_pk_bf16_f32 v2, v28, v10
	v_cvt_pk_bf16_f32 v3, v15, v12
	v_cvt_pk_bf16_f32 v4, v17, v7
	v_cvt_pk_bf16_f32 v5, v19, v9
	global_store_dwordx4 v[38:39], v[2:5], off offset:64
	s_cbranch_scc1 .LBB0_275
.LBB0_276:
	s_setprio 0
	s_cmp_lt_u32 s99, 5
	s_cbranch_scc1 .LBB0_288
	v_lshrrev_b32_e32 v2, 20, v0
	v_lshrrev_b32_e32 v3, 10, v0
	v_or_b32_e32 v2, v3, v2
	s_movk_i32 s0, 0x3ff
	v_and_or_b32 v2, v2, s0, v1
	v_cmp_eq_u32_e32 vcc, 0, v2
	s_waitcnt vmcnt(0)
	s_barrier
	s_and_saveexec_b64 s[0:1], vcc
	s_cbranch_execz .LBB0_287
	buffer_wbl2 sc1
	s_waitcnt vmcnt(0)
	v_readlane_b32 s6, v255, 60
	v_readlane_b32 s7, v255, 61
	v_readlane_b32 s8, v255, 63
	v_readlane_b32 s9, v255, 62
	s_add_u32 s6, s6, 0x7e00000
	s_addc_u32 s7, s7, 0
	s_and_b32 s10, s8, 7
	s_sub_i32 s11, s9, s10
	s_add_i32 s11, s11, 7
	s_lshr_b32 s11, s11, 3
	s_sub_i32 s11, 0x10001, s11
	s_cmp_lt_u32 s8, 8
	s_cselect_b32 s11, s11, 1
	s_lshl_b32 s8, s10, 8
	s_add_i32 s8, s8, 0x100
	v_mov_b32_e32 v2, s8
	v_mov_b32_e32 v3, s11
	global_atomic_add v3, v2, v3, s[6:7] sc0
	s_min_u32 s9, s9, 8
	s_sub_i32 s9, 0x10001, s9
	s_cmp_eq_u32 s10, 0
	s_cselect_b32 s9, s9, 1
	v_mov_b32_e32 v2, 0
	s_waitcnt vmcnt(0)
	v_readfirstlane_b32 s8, v3
	s_add_i32 s10, s8, s11
	s_xor_b32 s10, s10, s8
	s_lshr_b32 s10, s10, 16
	s_lshr_b32 s8, s8, 16
	s_cmp_eq_u32 s10, 0
	s_cbranch_scc1 .Lgb_poll_3
	v_mov_b32_e32 v3, s9
	global_atomic_add v2, v3, s[6:7]

.LBB0_506:
	s_andn2_b64 vcc, exec, s[4:5]
	s_cbranch_vccnz .LBB0_535
	v_mov_b32_e32 v0, v252
	s_andn2_b64 vcc, exec, s[12:13]
	s_cbranch_vccnz .LBB0_523
	v_readlane_b32 s4, v255, 2
	s_cmp_lt_u32 s4, 4
	s_cbranch_scc1 .Lprio_dil
	s_setprio 1
.Lprio_dil:
	v_lshlrev_b32_e32 v3, 4, v0
	v_ashrrev_i32_e32 v204, 4, v0
	v_lshlrev_b32_e32 v2, 3, v0
	v_and_b32_e32 v3, 0xc0, v3
	v_lshlrev_b32_e32 v5, 1, v0
	v_add_u32_e32 v207, 4, v204
	v_and_or_b32 v3, v2, 24, v3
	v_and_b32_e32 v5, 32, v5
	v_and_b32_e32 v2, 0x100, v2
	v_and_b32_e32 v10, 0xfffff0, v207
	v_lshlrev_b32_e32 v11, 1, v207
	v_or3_b32 v5, v3, v5, v2
	v_and_or_b32 v10, v11, 8, v10
	v_add_u32_e32 v203, s71, v5
	v_bfe_u32 v5, v0, 2, 2
	v_and_b32_e32 v7, 3, v204
	v_lshrrev_b32_e32 v11, 1, v207
	v_lshrrev_b32_e32 v10, 1, v10
	v_or_b32_e32 v10, v10, v5
	v_and_or_b32 v11, v11, 4, v7
	v_lshlrev_b32_e32 v10, 9, v10
	v_lshlrev_b32_e32 v11, 6, v11
	v_add_u32_e32 v208, 8, v204
	v_add3_u32 v10, s71, v11, v10
	v_and_b32_e32 v11, 0xfffff0, v208
	v_lshlrev_b32_e32 v12, 1, v208
	v_and_or_b32 v11, v12, 8, v11
	v_lshrrev_b32_e32 v12, 1, v208
	v_lshrrev_b32_e32 v11, 1, v11
	v_or_b32_e32 v11, v11, v5
	v_and_or_b32 v12, v12, 4, v7
	v_lshlrev_b32_e32 v11, 9, v11
	v_lshlrev_b32_e32 v12, 6, v12
	v_add_u32_e32 v209, 12, v204
	v_add3_u32 v11, s71, v12, v11
	v_and_b32_e32 v12, 0xfffff0, v209
	v_lshlrev_b32_e32 v13, 1, v209
	v_and_or_b32 v12, v13, 8, v12
	v_lshrrev_b32_e32 v13, 1, v209
	v_lshrrev_b32_e32 v12, 1, v12
	v_or_b32_e32 v12, v12, v5
	v_and_or_b32 v13, v13, 4, v7
	s_lshl_b32 s4, s84, 2
	v_lshlrev_b32_e32 v12, 9, v12
	v_lshlrev_b32_e32 v13, 6, v13
	v_add_u32_e32 v210, 16, v204
	v_and_b32_e32 v181, 31, v0
	v_ashrrev_i32_e32 v4, 5, v0
	s_or_b32 s33, s4, 1
	v_and_b32_e32 v6, 15, v0
	v_cmp_gt_u32_e64 s[6:7], 32, v0
	v_cmp_lt_u32_e64 s[4:5], 31, v0
	v_and_b32_e32 v0, 0xfffff0, v204
	v_lshlrev_b32_e32 v9, 1, v204
	v_add3_u32 v12, s71, v13, v12
	v_and_b32_e32 v13, 0xfffff0, v210
	v_lshlrev_b32_e32 v14, 1, v210
	v_and_or_b32 v0, v9, 8, v0
	v_lshrrev_b32_e32 v9, 1, v204
	v_and_or_b32 v13, v14, 8, v13
	v_lshrrev_b32_e32 v0, 1, v0
	v_and_or_b32 v9, v9, 4, v7
	v_lshrrev_b32_e32 v13, 1, v13
	v_or_b32_e32 v0, v0, v5
	v_lshl_add_u32 v9, v9, 6, s71
	v_or_b32_e32 v13, v13, v5
	v_add_u32_e32 v211, 20, v204
	v_lshl_add_u32 v0, v0, 9, v9
	v_lshl_add_u32 v9, v13, 9, v9
	v_and_b32_e32 v13, 0xfffff0, v211
	v_lshlrev_b32_e32 v14, 1, v211
	v_and_or_b32 v13, v14, 8, v13
	v_lshrrev_b32_e32 v14, 1, v211
	v_lshrrev_b32_e32 v13, 1, v13
	v_or_b32_e32 v13, v13, v5
	v_and_or_b32 v14, v14, 4, v7
	v_lshlrev_b32_e32 v13, 9, v13
	v_lshlrev_b32_e32 v14, 6, v14
	v_add_u32_e32 v212, 24, v204
	v_add3_u32 v13, s71, v14, v13
	v_and_b32_e32 v14, 0xfffff0, v212
	v_lshlrev_b32_e32 v15, 1, v212
	v_and_or_b32 v14, v15, 8, v14
	v_lshrrev_b32_e32 v15, 1, v212
	v_lshrrev_b32_e32 v14, 1, v14
	v_or_b32_e32 v14, v14, v5
	v_and_or_b32 v15, v15, 4, v7
	v_lshlrev_b32_e32 v14, 9, v14
	v_lshlrev_b32_e32 v15, 6, v15
	v_add_u32_e32 v213, 28, v204
	v_add3_u32 v14, s71, v15, v14
	v_and_b32_e32 v15, 0xfffff0, v213
	v_lshlrev_b32_e32 v16, 1, v213
	v_and_or_b32 v15, v16, 8, v15
	v_lshrrev_b32_e32 v16, 1, v213
	v_lshrrev_b32_e32 v15, 1, v15
	v_or_b32_e32 v5, v15, v5
	v_and_or_b32 v7, v16, 4, v7
	v_lshlrev_b32_e32 v205, 2, v4
	v_lshlrev_b32_e32 v5, 9, v5
	v_lshlrev_b32_e32 v7, 6, v7
	s_movk_i32 s8, 0x440
	v_lshlrev_b32_e32 v2, 3, v4
	v_add3_u32 v5, s71, v7, v5
	v_lshl_add_u32 v214, v4, 4, s71
	v_or_b32_e32 v7, 1, v205
	v_mul_lo_u32 v4, v4, s8
	s_movk_i32 s8, 0x110
	v_mul_lo_u32 v7, v7, s8
	v_lshlrev_b32_e32 v180, 3, v6
	v_lshlrev_b32_e32 v6, 4, v6
	v_add_u32_e32 v216, s71, v7
	v_ashrrev_i32_e32 v3, 31, v2
	v_and_b32_e32 v8, 48, v6
	v_lshlrev_b32_e32 v215, 1, v181
	v_add_u32_e32 v4, s71, v4
	v_add_u32_e32 v7, 0x110, v216
	v_add_u32_e32 v15, 0x220, v216
	v_add_u32_e32 v16, 0x770, v216
	v_add_u32_e32 v17, 0x880, v216
	v_add_u32_e32 v18, 0x990, v216
	v_add_u32_e32 v19, 0xaa0, v216
	v_add_u32_e32 v20, 0xff0, v216
	v_add_u32_e32 v21, 0x1100, v216
	v_add_u32_e32 v22, 0x1210, v216
	v_add_u32_e32 v23, 0x1320, v216
	v_add_u32_e32 v24, 0x1870, v216
	v_add_u32_e32 v25, 0x1980, v216
	v_add_u32_e32 v26, 0x1a90, v216
	v_add_u32_e32 v27, 0x1ba0, v216
	v_add_u32_e32 v6, s71, v6
	v_mul_lo_u32 v28, v204, s8
	v_lshl_add_u32 v206, v181, 2, s71
	v_sub_u32_e32 v217, 0, v205
	v_lshlrev_b64 v[182:183], 1, v[2:3]
	v_add_u32_e32 v218, v0, v8
	v_add_u32_e32 v219, v10, v8
	v_add_u32_e32 v220, v11, v8
	v_add_u32_e32 v221, v12, v8
	v_add_u32_e32 v222, v9, v8
	v_add_u32_e32 v223, v13, v8
	v_add_u32_e32 v224, v14, v8
	v_add_u32_e32 v225, v5, v8
	v_add_u32_e32 v226, v4, v215
	v_add_u32_e32 v227, v7, v215
	v_add_u32_e32 v228, v15, v215
	v_add_u32_e32 v229, v16, v215
	v_add_u32_e32 v230, v17, v215
	v_add_u32_e32 v231, v18, v215
	v_add_u32_e32 v232, v19, v215
	v_add_u32_e32 v233, v20, v215
	v_add_u32_e32 v234, v21, v215
	v_add_u32_e32 v235, v22, v215
	v_add_u32_e32 v236, v23, v215
	v_add_u32_e32 v237, v24, v215
	v_add_u32_e32 v238, v25, v215
	v_add_u32_e32 v239, v26, v215
	v_add_u32_e32 v240, v27, v215
	v_add_u32_e32 v241, v6, v28
	s_mov_b32 s54, s66
	s_branch .LBB0_510

.LBB0_523:
	s_setprio 0
	s_add_i32 s16, s85, 9
	s_cmp_lt_i32 s16, s99
	s_cbranch_scc0 .LBB0_535
	s_waitcnt vmcnt(0) lgkmcnt(0)
	s_barrier
	s_and_saveexec_b64 s[4:5], s[0:1]
	s_cbranch_execz .LBB0_534
	buffer_wbl2 sc1
	s_waitcnt vmcnt(0)
	v_readlane_b32 s6, v255, 60
	v_readlane_b32 s7, v255, 61
	v_readlane_b32 s8, v255, 63
	v_readlane_b32 s9, v255, 62
	s_add_u32 s6, s6, 0x7e00000
	s_addc_u32 s7, s7, 0
	s_and_b32 s10, s8, 7
	s_sub_i32 s11, s9, s10
	s_add_i32 s11, s11, 7
	s_lshr_b32 s11, s11, 3
	s_sub_i32 s11, 0x10001, s11
	s_cmp_lt_u32 s8, 8
	s_cselect_b32 s11, s11, 1
	s_lshl_b32 s8, s10, 8
	s_add_i32 s8, s8, 0x100
	v_mov_b32_e32 v2, s8
	v_mov_b32_e32 v3, s11
	global_atomic_add v3, v2, v3, s[6:7] sc0
	s_min_u32 s9, s9, 8
	s_sub_i32 s9, 0x10001, s9
	s_cmp_eq_u32 s10, 0
	s_cselect_b32 s9, s9, 1
	v_mov_b32_e32 v2, 0
	s_waitcnt vmcnt(0)
	v_readfirstlane_b32 s8, v3
	s_add_i32 s10, s8, s11
	s_xor_b32 s10, s10, s8
	s_lshr_b32 s10, s10, 16
	s_lshr_b32 s8, s8, 16
	s_cmp_eq_u32 s10, 0
	s_cbranch_scc1 .Lgb_poll_8
	v_mov_b32_e32 v3, s9
	global_atomic_add v2, v3, s[6:7]
